# rstd_lane: row-scale miss path in SwiGLU/in-proj epilogues does one load round per lane (fq-split) + LDS readback instead of 4 serialized rounds
# speedup vs baseline: 1.0068x; 1.0068x over previous
.LBB0_784:
	v_mbcnt_lo_u32_b32 v188, -1, 0
	v_mbcnt_hi_u32_b32 v188, -1, v188
	v_lshrrev_b32_e32 v188, 4, v188
	v_lshl_add_u32 v130, v188, 4, v158
	v_ashrrev_i32_e32 v131, 31, v130
	v_lshlrev_b64 v[130:131], 5, v[130:131]
	v_lshl_add_u64 v[138:139], s[74:75], 0, v[130:131]
	s_mov_b64 s[0:1], 0x277be800
	v_lshl_add_u64 v[144:145], v[138:139], 0, s[0:1]
	s_mov_b64 s[0:1], 0x277bf800
	v_lshl_add_u64 v[138:139], v[138:139], 0, s[0:1]
	global_load_dwordx4 v[130:133], v[144:145], off
	global_load_dwordx4 v[134:137], v[144:145], off offset:16
	global_load_dwordx4 v[140:143], v[138:139], off offset:16
	global_load_dwordx4 v[160:163], v[138:139], off
	s_mov_b32 s0, 0x358637bd
	v_mov_b64_e32 v[166:167], s[0:1]
	v_lshl_add_u32 v188, v188, 6, v0
	s_waitcnt vmcnt(0)
	v_mov_b32_e32 v164, v130
	v_mov_b32_e32 v165, v160
	v_mov_b32_e32 v160, v131
	v_pk_add_f32 v[130:131], v[164:165], v[160:161]
	v_mov_b32_e32 v160, v132
	v_mov_b32_e32 v161, v162
	v_mov_b32_e32 v162, v133
	v_pk_add_f32 v[132:133], v[160:161], v[162:163]
	s_nop 0
	v_pk_add_f32 v[130:131], v[130:131], v[132:133]
	v_mov_b32_e32 v132, v134
	v_mov_b32_e32 v133, v140
	v_mov_b32_e32 v140, v135
	v_mov_b32_e32 v134, v136
	v_mov_b32_e32 v135, v142
	v_mov_b32_e32 v142, v137
	v_pk_add_f32 v[132:133], v[132:133], v[140:141]
	v_pk_add_f32 v[134:135], v[134:135], v[142:143]
	s_nop 0
	v_pk_add_f32 v[132:133], v[132:133], v[134:135]
	s_nop 0
	v_pk_add_f32 v[130:131], v[130:131], v[132:133]
	s_nop 0
	v_pk_fma_f32 v[130:131], v[130:131], s[68:69], v[166:167] op_sel_hi:[1,0,0]
	s_nop 0
	v_mul_f32_e32 v132, 0x4b800000, v130
	v_cmp_gt_f32_e64 s[0:1], s92, v130
	v_cmp_gt_f32_e32 vcc, s92, v131
	s_nop 0
	v_cndmask_b32_e64 v130, v130, v132, s[0:1]
	v_mul_f32_e32 v132, 0x4b800000, v131
	v_cndmask_b32_e32 v131, v131, v132, vcc
	v_rsq_f32_e32 v130, v130
	v_rsq_f32_e32 v131, v131
	s_nop 0
	v_pk_mul_f32 v[132:133], v[130:131], s[94:95] op_sel_hi:[1,0]
	s_nop 0
	v_cndmask_b32_e32 v165, v131, v133, vcc
	v_cndmask_b32_e64 v164, v130, v132, s[0:1]
	v_mov_b32_e32 v130, s28
	v_mov_b32_e32 v131, s2
	ds_write2_b32 v188, v164, v165 offset1:128
	ds_write_b32 v130, v131

.LBB0_1396:
	s_mov_b64 s[20:21], s[62:63]
	v_mov_b32_e32 v130, v180
	v_mov_b32_e32 v184, v181
	v_mov_b32_e32 v131, s64
	ds_read_b32 v131, v131
	s_lshl_b32 s6, s66, 8
	s_add_i32 s6, s6, s33
	v_add_u32_e32 v176, s6, v130
	s_add_i32 s13, s66, 1
	s_waitcnt lgkmcnt(0)
	v_cmp_ne_u32_e32 vcc, s13, v131
	v_add_u32_e32 v172, 16, v176
	v_add_u32_e32 v168, 32, v176
	v_add_u32_e32 v164, 48, v176
	v_add_u32_e32 v162, 0x80, v176
	v_add_u32_e32 v160, 0x90, v176
	v_add_u32_e32 v158, 0xa0, v176
	v_add_u32_e32 v156, 0xb0, v176
	s_mov_b64 s[6:7], -1
	s_and_b64 vcc, exec, vcc
	v_ashrrev_i32_e32 v177, 31, v176
	v_lshl_add_u32 v185, v130, 2, s37
	v_ashrrev_i32_e32 v173, 31, v172
	v_ashrrev_i32_e32 v169, 31, v168
	v_ashrrev_i32_e32 v165, 31, v164
	v_ashrrev_i32_e32 v163, 31, v162
	v_ashrrev_i32_e32 v161, 31, v160
	v_ashrrev_i32_e32 v159, 31, v158
	v_ashrrev_i32_e32 v157, 31, v156
	s_mov_b32 s67, 0x18000
	s_mov_b32 s69, 0x8000
	s_cbranch_vccz .LBB0_1398
	s_add_u32 s22, s20, 0x277be800
	s_addc_u32 s23, s21, 0
	v_mbcnt_lo_u32_b32 v188, -1, 0
	v_mbcnt_hi_u32_b32 v188, -1, v188
	v_lshrrev_b32_e32 v188, 4, v188
	v_lshl_add_u32 v130, v188, 4, v176
	v_ashrrev_i32_e32 v131, 31, v130
	v_lshlrev_b64 v[130:131], 5, v[130:131]
	v_lshl_add_u64 v[134:135], s[22:23], 0, v[130:131]
	s_mov_b64 s[6:7], 0x1000
	v_lshl_add_u64 v[142:143], v[134:135], 0, s[6:7]
	global_load_dwordx4 v[130:133], v[134:135], off offset:16
	s_nop 0
	global_load_dwordx4 v[134:137], v[134:135], off
	s_nop 0
	global_load_dwordx4 v[138:141], v[142:143], off offset:16
	s_nop 0
	global_load_dwordx4 v[142:145], v[142:143], off
	s_mov_b64 s[6:7], -1
	s_mov_b32 s6, 0x358637bd
	v_mov_b64_e32 v[178:179], s[6:7]
	v_lshl_add_u32 v188, v188, 6, v185
	s_waitcnt vmcnt(0)
	v_mov_b32_e32 v167, v134
	v_mov_b32_e32 v166, v142
	v_mov_b32_e32 v134, v143
	v_mov_b32_e32 v142, v144
	v_mov_b32_e32 v143, v136
	v_mov_b32_e32 v136, v145
	v_pk_add_f32 v[134:135], v[166:167], v[134:135]
	v_pk_add_f32 v[136:137], v[142:143], v[136:137]
	s_nop 0
	v_pk_add_f32 v[134:135], v[134:135], v[136:137]
	v_mov_b32_e32 v136, v138
	v_mov_b32_e32 v137, v130
	v_mov_b32_e32 v130, v139
	v_pk_add_f32 v[130:131], v[136:137], v[130:131]
	v_mov_b32_e32 v136, v140
	v_mov_b32_e32 v137, v132
	v_mov_b32_e32 v132, v141
	v_pk_add_f32 v[132:133], v[136:137], v[132:133]
	s_nop 0
	v_pk_add_f32 v[130:131], v[130:131], v[132:133]
	s_nop 0
	v_pk_add_f32 v[130:131], v[134:135], v[130:131]
	s_nop 0
	v_pk_fma_f32 v[130:131], v[130:131], s[68:69], v[178:179] op_sel_hi:[1,0,0]
	s_nop 0
	v_mul_f32_e32 v132, 0x4b800000, v131
	v_cmp_gt_f32_e64 s[6:7], s92, v131
	v_cmp_gt_f32_e32 vcc, s92, v130
	s_nop 0
	v_cndmask_b32_e64 v131, v131, v132, s[6:7]
	v_mul_f32_e32 v132, 0x4b800000, v130
	v_cndmask_b32_e32 v130, v130, v132, vcc
	v_rsq_f32_e32 v131, v131
	v_rsq_f32_e32 v130, v130
	s_nop 0
	v_pk_mul_f32 v[132:133], v[130:131], s[94:95] op_sel_hi:[1,0]
	s_nop 0
	v_cndmask_b32_e64 v175, v131, v133, s[6:7]
	v_cndmask_b32_e32 v174, v130, v132, vcc
	v_mov_b32_e32 v132, s64
	v_mov_b32_e32 v133, s13
	ds_write2_b32 v188, v175, v174 offset1:128
	ds_write_b32 v132, v133
	s_mov_b64 s[6:7], -1
